# EpiResid rewritten by hand: rolling 3-group load pipeline (loads for group g+3 issued into freed accumulators)
# baseline (speedup 1.0000x reference)
; __device__ __forceinline__ unsigned cvt_pk_bf16(float lo, float hi) { const f32x2_t v = {lo, hi}; const bf16x2_t b = __builtin_convertvector(v, bf16x2_t); return __builtin_bit_cast(unsigned, b); }
;     __device__ __forceinline__ void operator()(AccRef acc, const Unit& u, int wr, int wc, int fr, int fq) const {
;         const int row0 = u.pm * BM + wr * 64 + fr, col0 = u.pn * BM + wc * 32 + 8 * fq;
; #pragma unroll
;         for (int ai = 0; ai < 2; ++ai)
; #pragma unroll
;           for (int mp = 0; mp < 2; ++mp) {
;             f32x4 hv[2][2][2];
; #pragma unroll
;             for (int mm = 0; mm < 2; ++mm) { const float* rowp = h + (size_t)(row0 + ai * HALF + (mp * 2 + mm) * 16) * DM + col0;
; #pragma unroll
;                 for (int bj = 0; bj < 2; ++bj) { hv[mm][bj][0] = *(const f32x4*)(rowp + bj * HALF); hv[mm][bj][1] = *(const f32x4*)(rowp + bj * HALF + 4); } }
; #pragma unroll
;             for (int mm = 0; mm < 2; ++mm) { const int m = mp * 2 + mm; const size_t row = (size_t)(row0 + ai * HALF + m * 16); float* rowp = h + row * DM + col0; bf16_t* rowb = hb + row * DM + col0; float ss = 0.f;
; #pragma unroll
;                 for (int bj = 0; bj < 2; ++bj) { const f32x4 a = hv[mm][bj][0] + acc[ai][bj][m][0] * scale, b = hv[mm][bj][1] + acc[ai][bj][m][1] * scale;
;                     __builtin_nontemporal_store(a, (f32x4*)(rowp + bj * HALF)); __builtin_nontemporal_store(b, (f32x4*)(rowp + bj * HALF + 4));
;                     ss += (a[0] * a[0] + a[1] * a[1]) + (a[2] * a[2] + a[3] * a[3]) + (b[0] * b[0] + b[1] * b[1]) + (b[2] * b[2] + b[3] * b[3]);
;                     u32x4 w; w.x = cvt_pk_bf16(a[0], a[1]); w.y = cvt_pk_bf16(a[2], a[3]); w.z = cvt_pk_bf16(b[0], b[1]); w.w = cvt_pk_bf16(b[2], b[3]);
;                     *(u32x4*)(rowb + bj * HALF) = w; }
;                 ss += __shfl_xor(ss, 16); ss += __shfl_xor(ss, 32);
;                 if (fq == 0) part[row * 16 + u.pn * 4 + wc] = ss; } }
.LBB0_482:
	s_and_b64 vcc, exec, s[22:23]
	s_cbranch_vccz .LBB0_503
	s_cmp_gt_i32 s5, 0
	s_mov_b64 s[22:23], -1
	s_cbranch_scc0 .LBB0_501
	v_ashrrev_i32_e32 v221, 31, v220
	v_ashrrev_i32_e32 v219, 31, v218
	v_xor_b32_e32 v222, 16, v243
	v_xor_b32_e32 v223, 32, v243
	v_lshlrev_b32_e32 v222, 2, v222
	v_lshlrev_b32_e32 v223, 2, v223
	v_lshlrev_b64 v[176:177], 12, v[218:219]
	v_lshlrev_b64 v[224:225], 2, v[220:221]
	v_lshl_add_u64 v[176:177], s[44:45], 0, v[176:177]
	v_lshl_add_u64 v[176:177], v[176:177], 0, v[224:225]
	s_mov_b32 s101, 0
	global_load_dwordx4 v[128:131], v[176:177], off
	global_load_dwordx4 v[132:135], v[176:177], off offset:16
	global_load_dwordx4 v[136:139], v[176:177], off offset:512
	global_load_dwordx4 v[140:143], v[176:177], off offset:528
	s_mov_b32 s100, 0x10000
	v_lshl_add_u64 v[176:177], v[176:177], 0, s[100:101]
	global_load_dwordx4 v[144:147], v[176:177], off
	global_load_dwordx4 v[148:151], v[176:177], off offset:16
	global_load_dwordx4 v[152:155], v[176:177], off offset:512
	global_load_dwordx4 v[156:159], v[176:177], off offset:528
	s_mov_b32 s100, 0x10000
	v_lshl_add_u64 v[176:177], v[176:177], 0, s[100:101]
	global_load_dwordx4 v[160:163], v[176:177], off
	global_load_dwordx4 v[164:167], v[176:177], off offset:16
	global_load_dwordx4 v[168:171], v[176:177], off offset:512
	global_load_dwordx4 v[172:175], v[176:177], off offset:528
	s_mov_b32 s100, 0x10000
	v_lshl_add_u64 v[176:177], v[176:177], 0, s[100:101]
	v_lshlrev_b64 v[178:179], 12, v[218:219]
	v_lshl_add_u64 v[178:179], s[44:45], 0, v[178:179]
	v_lshl_add_u64 v[178:179], v[178:179], 0, v[224:225]
	v_lshlrev_b64 v[180:181], 11, v[218:219]
	v_lshl_add_u64 v[180:181], s[52:53], 0, v[180:181]
	v_lshl_add_u64 v[180:181], v[220:221], 1, v[180:181]
	v_lshlrev_b64 v[182:183], 6, v[218:219]
	v_lshl_add_u64 v[182:183], s[20:21], 0, v[182:183]
	s_lshl_b32 s98, s70, 4
	s_lshl_b32 s99, s64, 2
	s_add_u32 s98, s98, s99
	s_mov_b32 s99, 0
	v_lshl_add_u64 v[182:183], v[182:183], 0, s[98:99]
	s_waitcnt vmcnt(8)
	v_pk_fma_f32 v[128:129], s[58:59], v[124:125], v[128:129]
	v_pk_fma_f32 v[130:131], s[16:17], v[126:127], v[130:131]
	v_pk_fma_f32 v[132:133], s[58:59], v[120:121], v[132:133]
	v_pk_fma_f32 v[134:135], s[16:17], v[122:123], v[134:135]
	v_pk_fma_f32 v[136:137], s[58:59], v[116:117], v[136:137]
	v_pk_fma_f32 v[138:139], s[16:17], v[118:119], v[138:139]
	v_pk_fma_f32 v[140:141], s[58:59], v[112:113], v[140:141]
	v_pk_fma_f32 v[142:143], s[16:17], v[114:115], v[142:143]
	global_load_dwordx4 v[124:127], v[176:177], off
	global_load_dwordx4 v[120:123], v[176:177], off offset:16
	global_load_dwordx4 v[116:119], v[176:177], off offset:512
	global_load_dwordx4 v[112:115], v[176:177], off offset:528
	s_mov_b32 s100, 0x50000
	v_lshl_add_u64 v[176:177], v[176:177], 0, s[100:101]
	global_store_dwordx4 v[178:179], v[128:131], off nt
	global_store_dwordx4 v[178:179], v[132:135], off offset:16 nt
	v_mul_f32_e32 v225, v131, v131
	v_mul_f32_e32 v224, v129, v129
	v_fmac_f32_e32 v224, v128, v128
	v_fmac_f32_e32 v225, v130, v130
	v_add_f32_e32 v224, v224, v225
	v_mul_f32_e32 v225, v133, v133
	v_fmac_f32_e32 v225, v132, v132
	v_add_f32_e32 v224, v225, v224
	v_mul_f32_e32 v225, v135, v135
	v_fmac_f32_e32 v225, v134, v134
	v_add_f32_e32 v224, v225, v224
	v_cvt_pk_bf16_f32 v226, v128, v129
	v_cvt_pk_bf16_f32 v227, v130, v131
	v_cvt_pk_bf16_f32 v228, v132, v133
	v_cvt_pk_bf16_f32 v229, v134, v135
	global_store_dwordx4 v[180:181], v[226:229], off
	global_store_dwordx4 v[178:179], v[136:139], off offset:512 nt
	global_store_dwordx4 v[178:179], v[140:143], off offset:528 nt
	v_mul_f32_e32 v232, v137, v137
	v_mul_f32_e32 v233, v139, v139
	v_fmac_f32_e32 v232, v136, v136
	v_fmac_f32_e32 v233, v138, v138
	v_add_f32_e32 v232, v232, v233
	v_mul_f32_e32 v233, v141, v141
	v_fmac_f32_e32 v233, v140, v140
	v_add_f32_e32 v232, v233, v232
	v_mul_f32_e32 v233, v143, v143
	v_fmac_f32_e32 v233, v142, v142
	v_add_f32_e32 v232, v233, v232
	v_add_f32_e32 v224, v224, v232
	ds_bpermute_b32 v230, v222, v224
	v_cvt_pk_bf16_f32 v226, v136, v137
	v_cvt_pk_bf16_f32 v227, v138, v139
	v_cvt_pk_bf16_f32 v228, v140, v141
	v_cvt_pk_bf16_f32 v229, v142, v143
	global_store_dwordx4 v[180:181], v[226:229], off offset:256
	s_mov_b32 s100, 0x10000
	v_lshl_add_u64 v[178:179], v[178:179], 0, s[100:101]
	s_mov_b32 s100, 0x8000
	v_lshl_add_u64 v[180:181], v[180:181], 0, s[100:101]
	s_waitcnt lgkmcnt(0)
	v_add_f32_e32 v224, v224, v230
	ds_bpermute_b32 v231, v223, v224
	s_waitcnt lgkmcnt(0)
	v_add_f32_e32 v224, v224, v231
	s_and_saveexec_b64 s[6:7], s[8:9]
	global_store_dword v[182:183], v224, off
	s_or_b64 exec, exec, s[6:7]
	s_mov_b32 s100, 0x400
	v_lshl_add_u64 v[182:183], v[182:183], 0, s[100:101]
	s_waitcnt vmcnt(15)
; __device__ __forceinline__ unsigned cvt_pk_bf16(float lo, float hi) { const f32x2_t v = {lo, hi}; const bf16x2_t b = __builtin_convertvector(v, bf16x2_t); return __builtin_bit_cast(unsigned, b); }
;     __device__ __forceinline__ void operator()(AccRef acc, const Unit& u, int wr, int wc, int fr, int fq) const {
;     ...
;             for (int mm = 0; mm < 2; ++mm) { const float* rowp = h + (size_t)(row0 + ai * HALF + (mp * 2 + mm) * 16) * DM + col0;
; #pragma unroll
;                 for (int bj = 0; bj < 2; ++bj) { hv[mm][bj][0] = *(const f32x4*)(rowp + bj * HALF); hv[mm][bj][1] = *(const f32x4*)(rowp + bj * HALF + 4); } }
; #pragma unroll
;             for (int mm = 0; mm < 2; ++mm) { const int m = mp * 2 + mm; const size_t row = (size_t)(row0 + ai * HALF + m * 16); float* rowp = h + row * DM + col0; bf16_t* rowb = hb + row * DM + col0; float ss = 0.f;
; #pragma unroll
;                 for (int bj = 0; bj < 2; ++bj) { const f32x4 a = hv[mm][bj][0] + acc[ai][bj][m][0] * scale, b = hv[mm][bj][1] + acc[ai][bj][m][1] * scale;
;                     __builtin_nontemporal_store(a, (f32x4*)(rowp + bj * HALF)); __builtin_nontemporal_store(b, (f32x4*)(rowp + bj * HALF + 4));
;                     ss += (a[0] * a[0] + a[1] * a[1]) + (a[2] * a[2] + a[3] * a[3]) + (b[0] * b[0] + b[1] * b[1]) + (b[2] * b[2] + b[3] * b[3]);
;                     u32x4 w; w.x = cvt_pk_bf16(a[0], a[1]); w.y = cvt_pk_bf16(a[2], a[3]); w.z = cvt_pk_bf16(b[0], b[1]); w.w = cvt_pk_bf16(b[2], b[3]);
;                     *(u32x4*)(rowb + bj * HALF) = w; }
;                 ss += __shfl_xor(ss, 16); ss += __shfl_xor(ss, 32);
;                 if (fq == 0) part[row * 16 + u.pn * 4 + wc] = ss; } }
	v_pk_fma_f32 v[144:145], s[58:59], v[108:109], v[144:145]
	v_pk_fma_f32 v[146:147], s[16:17], v[110:111], v[146:147]
	v_pk_fma_f32 v[148:149], s[58:59], v[104:105], v[148:149]
	v_pk_fma_f32 v[150:151], s[16:17], v[106:107], v[150:151]
	v_pk_fma_f32 v[152:153], s[58:59], v[100:101], v[152:153]
	v_pk_fma_f32 v[154:155], s[16:17], v[102:103], v[154:155]
	v_pk_fma_f32 v[156:157], s[58:59], v[96:97], v[156:157]
	v_pk_fma_f32 v[158:159], s[16:17], v[98:99], v[158:159]
	global_load_dwordx4 v[108:111], v[176:177], off
	global_load_dwordx4 v[104:107], v[176:177], off offset:16
	global_load_dwordx4 v[100:103], v[176:177], off offset:512
	global_load_dwordx4 v[96:99], v[176:177], off offset:528
	s_mov_b32 s100, 0x10000
	v_lshl_add_u64 v[176:177], v[176:177], 0, s[100:101]
	global_store_dwordx4 v[178:179], v[144:147], off nt
	global_store_dwordx4 v[178:179], v[148:151], off offset:16 nt
	v_mul_f32_e32 v225, v147, v147
	v_mul_f32_e32 v224, v145, v145
	v_fmac_f32_e32 v224, v144, v144
	v_fmac_f32_e32 v225, v146, v146
	v_add_f32_e32 v224, v224, v225
	v_mul_f32_e32 v225, v149, v149
	v_fmac_f32_e32 v225, v148, v148
	v_add_f32_e32 v224, v225, v224
	v_mul_f32_e32 v225, v151, v151
	v_fmac_f32_e32 v225, v150, v150
	v_add_f32_e32 v224, v225, v224
	v_cvt_pk_bf16_f32 v226, v144, v145
	v_cvt_pk_bf16_f32 v227, v146, v147
	v_cvt_pk_bf16_f32 v228, v148, v149
	v_cvt_pk_bf16_f32 v229, v150, v151
	global_store_dwordx4 v[180:181], v[226:229], off
	global_store_dwordx4 v[178:179], v[152:155], off offset:512 nt
	global_store_dwordx4 v[178:179], v[156:159], off offset:528 nt
	v_mul_f32_e32 v232, v153, v153
	v_mul_f32_e32 v233, v155, v155
	v_fmac_f32_e32 v232, v152, v152
	v_fmac_f32_e32 v233, v154, v154
	v_add_f32_e32 v232, v232, v233
	v_mul_f32_e32 v233, v157, v157
	v_fmac_f32_e32 v233, v156, v156
	v_add_f32_e32 v232, v233, v232
	v_mul_f32_e32 v233, v159, v159
	v_fmac_f32_e32 v233, v158, v158
	v_add_f32_e32 v232, v233, v232
	v_add_f32_e32 v224, v224, v232
	ds_bpermute_b32 v230, v222, v224
	v_cvt_pk_bf16_f32 v226, v152, v153
	v_cvt_pk_bf16_f32 v227, v154, v155
	v_cvt_pk_bf16_f32 v228, v156, v157
	v_cvt_pk_bf16_f32 v229, v158, v159
	global_store_dwordx4 v[180:181], v[226:229], off offset:256
	s_mov_b32 s100, 0x10000
	v_lshl_add_u64 v[178:179], v[178:179], 0, s[100:101]
	s_mov_b32 s100, 0x8000
	v_lshl_add_u64 v[180:181], v[180:181], 0, s[100:101]
	s_waitcnt lgkmcnt(0)
	v_add_f32_e32 v224, v224, v230
	ds_bpermute_b32 v231, v223, v224
	s_waitcnt lgkmcnt(0)
	v_add_f32_e32 v224, v224, v231
	s_and_saveexec_b64 s[6:7], s[8:9]
	global_store_dword v[182:183], v224, off
	s_or_b64 exec, exec, s[6:7]
	s_mov_b32 s100, 0x400
	v_lshl_add_u64 v[182:183], v[182:183], 0, s[100:101]
	s_waitcnt vmcnt(22)
	v_pk_fma_f32 v[160:161], s[58:59], v[92:93], v[160:161]
	v_pk_fma_f32 v[162:163], s[16:17], v[94:95], v[162:163]
	v_pk_fma_f32 v[164:165], s[58:59], v[88:89], v[164:165]
	v_pk_fma_f32 v[166:167], s[16:17], v[90:91], v[166:167]
	v_pk_fma_f32 v[168:169], s[58:59], v[84:85], v[168:169]
	v_pk_fma_f32 v[170:171], s[16:17], v[86:87], v[170:171]
	v_pk_fma_f32 v[172:173], s[58:59], v[80:81], v[172:173]
	v_pk_fma_f32 v[174:175], s[16:17], v[82:83], v[174:175]
	global_load_dwordx4 v[92:95], v[176:177], off
	global_load_dwordx4 v[88:91], v[176:177], off offset:16
	global_load_dwordx4 v[84:87], v[176:177], off offset:512
	global_load_dwordx4 v[80:83], v[176:177], off offset:528
	s_mov_b32 s100, 0x10000
	v_lshl_add_u64 v[176:177], v[176:177], 0, s[100:101]
	global_store_dwordx4 v[178:179], v[160:163], off nt
	global_store_dwordx4 v[178:179], v[164:167], off offset:16 nt
	v_mul_f32_e32 v225, v163, v163
	v_mul_f32_e32 v224, v161, v161
	v_fmac_f32_e32 v224, v160, v160
	v_fmac_f32_e32 v225, v162, v162
	v_add_f32_e32 v224, v224, v225
	v_mul_f32_e32 v225, v165, v165
	v_fmac_f32_e32 v225, v164, v164
	v_add_f32_e32 v224, v225, v224
	v_mul_f32_e32 v225, v167, v167
	v_fmac_f32_e32 v225, v166, v166
	v_add_f32_e32 v224, v225, v224
	v_cvt_pk_bf16_f32 v226, v160, v161
	v_cvt_pk_bf16_f32 v227, v162, v163
	v_cvt_pk_bf16_f32 v228, v164, v165
	v_cvt_pk_bf16_f32 v229, v166, v167
	global_store_dwordx4 v[180:181], v[226:229], off
	global_store_dwordx4 v[178:179], v[168:171], off offset:512 nt
	global_store_dwordx4 v[178:179], v[172:175], off offset:528 nt
	v_mul_f32_e32 v232, v169, v169
	v_mul_f32_e32 v233, v171, v171
	v_fmac_f32_e32 v232, v168, v168
	v_fmac_f32_e32 v233, v170, v170
	v_add_f32_e32 v232, v232, v233
	v_mul_f32_e32 v233, v173, v173
	v_fmac_f32_e32 v233, v172, v172
	v_add_f32_e32 v232, v233, v232
	v_mul_f32_e32 v233, v175, v175
	v_fmac_f32_e32 v233, v174, v174
	v_add_f32_e32 v232, v233, v232
	v_add_f32_e32 v224, v224, v232
	ds_bpermute_b32 v230, v222, v224
	v_cvt_pk_bf16_f32 v226, v168, v169
	v_cvt_pk_bf16_f32 v227, v170, v171
	v_cvt_pk_bf16_f32 v228, v172, v173
	v_cvt_pk_bf16_f32 v229, v174, v175
	global_store_dwordx4 v[180:181], v[226:229], off offset:256
	s_mov_b32 s100, 0x10000
	v_lshl_add_u64 v[178:179], v[178:179], 0, s[100:101]
	s_mov_b32 s100, 0x8000
	v_lshl_add_u64 v[180:181], v[180:181], 0, s[100:101]
	s_waitcnt lgkmcnt(0)
	v_add_f32_e32 v224, v224, v230
	ds_bpermute_b32 v231, v223, v224
	s_waitcnt lgkmcnt(0)
	v_add_f32_e32 v224, v224, v231
	s_and_saveexec_b64 s[6:7], s[8:9]
	global_store_dword v[182:183], v224, off
	s_or_b64 exec, exec, s[6:7]
	s_mov_b32 s100, 0x400
	v_lshl_add_u64 v[182:183], v[182:183], 0, s[100:101]
	s_waitcnt vmcnt(29)
; __device__ __forceinline__ unsigned cvt_pk_bf16(float lo, float hi) { const f32x2_t v = {lo, hi}; const bf16x2_t b = __builtin_convertvector(v, bf16x2_t); return __builtin_bit_cast(unsigned, b); }
;     __device__ __forceinline__ void operator()(AccRef acc, const Unit& u, int wr, int wc, int fr, int fq) const {
;     ...
;             for (int mm = 0; mm < 2; ++mm) { const float* rowp = h + (size_t)(row0 + ai * HALF + (mp * 2 + mm) * 16) * DM + col0;
; #pragma unroll
;                 for (int bj = 0; bj < 2; ++bj) { hv[mm][bj][0] = *(const f32x4*)(rowp + bj * HALF); hv[mm][bj][1] = *(const f32x4*)(rowp + bj * HALF + 4); } }
; #pragma unroll
;             for (int mm = 0; mm < 2; ++mm) { const int m = mp * 2 + mm; const size_t row = (size_t)(row0 + ai * HALF + m * 16); float* rowp = h + row * DM + col0; bf16_t* rowb = hb + row * DM + col0; float ss = 0.f;
; #pragma unroll
;                 for (int bj = 0; bj < 2; ++bj) { const f32x4 a = hv[mm][bj][0] + acc[ai][bj][m][0] * scale, b = hv[mm][bj][1] + acc[ai][bj][m][1] * scale;
;                     __builtin_nontemporal_store(a, (f32x4*)(rowp + bj * HALF)); __builtin_nontemporal_store(b, (f32x4*)(rowp + bj * HALF + 4));
;                     ss += (a[0] * a[0] + a[1] * a[1]) + (a[2] * a[2] + a[3] * a[3]) + (b[0] * b[0] + b[1] * b[1]) + (b[2] * b[2] + b[3] * b[3]);
;                     u32x4 w; w.x = cvt_pk_bf16(a[0], a[1]); w.y = cvt_pk_bf16(a[2], a[3]); w.z = cvt_pk_bf16(b[0], b[1]); w.w = cvt_pk_bf16(b[2], b[3]);
;                     *(u32x4*)(rowb + bj * HALF) = w; }
;                 ss += __shfl_xor(ss, 16); ss += __shfl_xor(ss, 32);
;                 if (fq == 0) part[row * 16 + u.pn * 4 + wc] = ss; } }
	v_pk_fma_f32 v[124:125], s[58:59], v[76:77], v[124:125]
	v_pk_fma_f32 v[126:127], s[16:17], v[78:79], v[126:127]
	v_pk_fma_f32 v[120:121], s[58:59], v[72:73], v[120:121]
	v_pk_fma_f32 v[122:123], s[16:17], v[74:75], v[122:123]
	v_pk_fma_f32 v[116:117], s[58:59], v[68:69], v[116:117]
	v_pk_fma_f32 v[118:119], s[16:17], v[70:71], v[118:119]
	v_pk_fma_f32 v[112:113], s[58:59], v[64:65], v[112:113]
	v_pk_fma_f32 v[114:115], s[16:17], v[66:67], v[114:115]
	global_load_dwordx4 v[76:79], v[176:177], off
	global_load_dwordx4 v[72:75], v[176:177], off offset:16
	global_load_dwordx4 v[68:71], v[176:177], off offset:512
	global_load_dwordx4 v[64:67], v[176:177], off offset:528
	s_mov_b32 s100, 0x10000
	v_lshl_add_u64 v[176:177], v[176:177], 0, s[100:101]
	global_store_dwordx4 v[178:179], v[124:127], off nt
	global_store_dwordx4 v[178:179], v[120:123], off offset:16 nt
	v_mul_f32_e32 v225, v127, v127
	v_mul_f32_e32 v224, v125, v125
	v_fmac_f32_e32 v224, v124, v124
	v_fmac_f32_e32 v225, v126, v126
	v_add_f32_e32 v224, v224, v225
	v_mul_f32_e32 v225, v121, v121
	v_fmac_f32_e32 v225, v120, v120
	v_add_f32_e32 v224, v225, v224
	v_mul_f32_e32 v225, v123, v123
	v_fmac_f32_e32 v225, v122, v122
	v_add_f32_e32 v224, v225, v224
	v_cvt_pk_bf16_f32 v226, v124, v125
	v_cvt_pk_bf16_f32 v227, v126, v127
	v_cvt_pk_bf16_f32 v228, v120, v121
	v_cvt_pk_bf16_f32 v229, v122, v123
	global_store_dwordx4 v[180:181], v[226:229], off
	global_store_dwordx4 v[178:179], v[116:119], off offset:512 nt
	global_store_dwordx4 v[178:179], v[112:115], off offset:528 nt
	v_mul_f32_e32 v232, v117, v117
	v_mul_f32_e32 v233, v119, v119
	v_fmac_f32_e32 v232, v116, v116
	v_fmac_f32_e32 v233, v118, v118
	v_add_f32_e32 v232, v232, v233
	v_mul_f32_e32 v233, v113, v113
	v_fmac_f32_e32 v233, v112, v112
	v_add_f32_e32 v232, v233, v232
	v_mul_f32_e32 v233, v115, v115
	v_fmac_f32_e32 v233, v114, v114
	v_add_f32_e32 v232, v233, v232
	v_add_f32_e32 v224, v224, v232
	ds_bpermute_b32 v230, v222, v224
	v_cvt_pk_bf16_f32 v226, v116, v117
	v_cvt_pk_bf16_f32 v227, v118, v119
	v_cvt_pk_bf16_f32 v228, v112, v113
	v_cvt_pk_bf16_f32 v229, v114, v115
	global_store_dwordx4 v[180:181], v[226:229], off offset:256
	s_mov_b32 s100, 0x50000
	v_lshl_add_u64 v[178:179], v[178:179], 0, s[100:101]
	s_mov_b32 s100, 0x28000
	v_lshl_add_u64 v[180:181], v[180:181], 0, s[100:101]
	s_waitcnt lgkmcnt(0)
	v_add_f32_e32 v224, v224, v230
	ds_bpermute_b32 v231, v223, v224
	s_waitcnt lgkmcnt(0)
	v_add_f32_e32 v224, v224, v231
	s_and_saveexec_b64 s[6:7], s[8:9]
	global_store_dword v[182:183], v224, off
	s_or_b64 exec, exec, s[6:7]
	s_mov_b32 s100, 0x1400
	v_lshl_add_u64 v[182:183], v[182:183], 0, s[100:101]
	s_waitcnt vmcnt(29)
	v_pk_fma_f32 v[108:109], s[58:59], v[60:61], v[108:109]
	v_pk_fma_f32 v[110:111], s[16:17], v[62:63], v[110:111]
	v_pk_fma_f32 v[104:105], s[58:59], v[56:57], v[104:105]
	v_pk_fma_f32 v[106:107], s[16:17], v[58:59], v[106:107]
	v_pk_fma_f32 v[100:101], s[58:59], v[52:53], v[100:101]
	v_pk_fma_f32 v[102:103], s[16:17], v[54:55], v[102:103]
	v_pk_fma_f32 v[96:97], s[58:59], v[48:49], v[96:97]
	v_pk_fma_f32 v[98:99], s[16:17], v[50:51], v[98:99]
	global_load_dwordx4 v[60:63], v[176:177], off
	global_load_dwordx4 v[56:59], v[176:177], off offset:16
	global_load_dwordx4 v[52:55], v[176:177], off offset:512
	global_load_dwordx4 v[48:51], v[176:177], off offset:528
	global_store_dwordx4 v[178:179], v[108:111], off nt
	global_store_dwordx4 v[178:179], v[104:107], off offset:16 nt
	v_mul_f32_e32 v225, v111, v111
	v_mul_f32_e32 v224, v109, v109
	v_fmac_f32_e32 v224, v108, v108
	v_fmac_f32_e32 v225, v110, v110
	v_add_f32_e32 v224, v224, v225
	v_mul_f32_e32 v225, v105, v105
	v_fmac_f32_e32 v225, v104, v104
	v_add_f32_e32 v224, v225, v224
	v_mul_f32_e32 v225, v107, v107
	v_fmac_f32_e32 v225, v106, v106
	v_add_f32_e32 v224, v225, v224
	v_cvt_pk_bf16_f32 v226, v108, v109
	v_cvt_pk_bf16_f32 v227, v110, v111
	v_cvt_pk_bf16_f32 v228, v104, v105
	v_cvt_pk_bf16_f32 v229, v106, v107
	global_store_dwordx4 v[180:181], v[226:229], off
	global_store_dwordx4 v[178:179], v[100:103], off offset:512 nt
	global_store_dwordx4 v[178:179], v[96:99], off offset:528 nt
	v_mul_f32_e32 v232, v101, v101
	v_mul_f32_e32 v233, v103, v103
	v_fmac_f32_e32 v232, v100, v100
	v_fmac_f32_e32 v233, v102, v102
	v_add_f32_e32 v232, v232, v233
	v_mul_f32_e32 v233, v97, v97
	v_fmac_f32_e32 v233, v96, v96
	v_add_f32_e32 v232, v233, v232
	v_mul_f32_e32 v233, v99, v99
	v_fmac_f32_e32 v233, v98, v98
	v_add_f32_e32 v232, v233, v232
	v_add_f32_e32 v224, v224, v232
	ds_bpermute_b32 v230, v222, v224
	v_cvt_pk_bf16_f32 v226, v100, v101
	v_cvt_pk_bf16_f32 v227, v102, v103
	v_cvt_pk_bf16_f32 v228, v96, v97
	v_cvt_pk_bf16_f32 v229, v98, v99
	global_store_dwordx4 v[180:181], v[226:229], off offset:256
	s_mov_b32 s100, 0x10000
	v_lshl_add_u64 v[178:179], v[178:179], 0, s[100:101]
	s_mov_b32 s100, 0x8000
	v_lshl_add_u64 v[180:181], v[180:181], 0, s[100:101]
	s_waitcnt lgkmcnt(0)
	v_add_f32_e32 v224, v224, v230
	ds_bpermute_b32 v231, v223, v224
	s_waitcnt lgkmcnt(0)
	v_add_f32_e32 v224, v224, v231
	s_and_saveexec_b64 s[6:7], s[8:9]
	global_store_dword v[182:183], v224, off
	s_or_b64 exec, exec, s[6:7]
	s_mov_b32 s100, 0x400
	v_lshl_add_u64 v[182:183], v[182:183], 0, s[100:101]
	s_waitcnt vmcnt(29)
; __device__ __forceinline__ unsigned cvt_pk_bf16(float lo, float hi) { const f32x2_t v = {lo, hi}; const bf16x2_t b = __builtin_convertvector(v, bf16x2_t); return __builtin_bit_cast(unsigned, b); }
;     __device__ __forceinline__ void operator()(AccRef acc, const Unit& u, int wr, int wc, int fr, int fq) const {
;     ...
;             for (int mm = 0; mm < 2; ++mm) { const float* rowp = h + (size_t)(row0 + ai * HALF + (mp * 2 + mm) * 16) * DM + col0;
; #pragma unroll
;                 for (int bj = 0; bj < 2; ++bj) { hv[mm][bj][0] = *(const f32x4*)(rowp + bj * HALF); hv[mm][bj][1] = *(const f32x4*)(rowp + bj * HALF + 4); } }
; #pragma unroll
;             for (int mm = 0; mm < 2; ++mm) { const int m = mp * 2 + mm; const size_t row = (size_t)(row0 + ai * HALF + m * 16); float* rowp = h + row * DM + col0; bf16_t* rowb = hb + row * DM + col0; float ss = 0.f;
; #pragma unroll
;                 for (int bj = 0; bj < 2; ++bj) { const f32x4 a = hv[mm][bj][0] + acc[ai][bj][m][0] * scale, b = hv[mm][bj][1] + acc[ai][bj][m][1] * scale;
;                     __builtin_nontemporal_store(a, (f32x4*)(rowp + bj * HALF)); __builtin_nontemporal_store(b, (f32x4*)(rowp + bj * HALF + 4));
;                     ss += (a[0] * a[0] + a[1] * a[1]) + (a[2] * a[2] + a[3] * a[3]) + (b[0] * b[0] + b[1] * b[1]) + (b[2] * b[2] + b[3] * b[3]);
;                     u32x4 w; w.x = cvt_pk_bf16(a[0], a[1]); w.y = cvt_pk_bf16(a[2], a[3]); w.z = cvt_pk_bf16(b[0], b[1]); w.w = cvt_pk_bf16(b[2], b[3]);
;                     *(u32x4*)(rowb + bj * HALF) = w; }
;                 ss += __shfl_xor(ss, 16); ss += __shfl_xor(ss, 32);
;                 if (fq == 0) part[row * 16 + u.pn * 4 + wc] = ss; } }
	v_pk_fma_f32 v[92:93], s[58:59], v[44:45], v[92:93]
	v_pk_fma_f32 v[94:95], s[16:17], v[46:47], v[94:95]
	v_pk_fma_f32 v[88:89], s[58:59], v[40:41], v[88:89]
	v_pk_fma_f32 v[90:91], s[16:17], v[42:43], v[90:91]
	v_pk_fma_f32 v[84:85], s[58:59], v[36:37], v[84:85]
	v_pk_fma_f32 v[86:87], s[16:17], v[38:39], v[86:87]
	v_pk_fma_f32 v[80:81], s[58:59], v[32:33], v[80:81]
	v_pk_fma_f32 v[82:83], s[16:17], v[34:35], v[82:83]
	global_store_dwordx4 v[178:179], v[92:95], off nt
	global_store_dwordx4 v[178:179], v[88:91], off offset:16 nt
	v_mul_f32_e32 v225, v95, v95
	v_mul_f32_e32 v224, v93, v93
	v_fmac_f32_e32 v224, v92, v92
	v_fmac_f32_e32 v225, v94, v94
	v_add_f32_e32 v224, v224, v225
	v_mul_f32_e32 v225, v89, v89
	v_fmac_f32_e32 v225, v88, v88
	v_add_f32_e32 v224, v225, v224
	v_mul_f32_e32 v225, v91, v91
	v_fmac_f32_e32 v225, v90, v90
	v_add_f32_e32 v224, v225, v224
	v_cvt_pk_bf16_f32 v226, v92, v93
	v_cvt_pk_bf16_f32 v227, v94, v95
	v_cvt_pk_bf16_f32 v228, v88, v89
	v_cvt_pk_bf16_f32 v229, v90, v91
	global_store_dwordx4 v[180:181], v[226:229], off
	global_store_dwordx4 v[178:179], v[84:87], off offset:512 nt
	global_store_dwordx4 v[178:179], v[80:83], off offset:528 nt
	v_mul_f32_e32 v232, v85, v85
	v_mul_f32_e32 v233, v87, v87
	v_fmac_f32_e32 v232, v84, v84
	v_fmac_f32_e32 v233, v86, v86
	v_add_f32_e32 v232, v232, v233
	v_mul_f32_e32 v233, v81, v81
	v_fmac_f32_e32 v233, v80, v80
	v_add_f32_e32 v232, v233, v232
	v_mul_f32_e32 v233, v83, v83
	v_fmac_f32_e32 v233, v82, v82
	v_add_f32_e32 v232, v233, v232
	v_add_f32_e32 v224, v224, v232
	ds_bpermute_b32 v230, v222, v224
	v_cvt_pk_bf16_f32 v226, v84, v85
	v_cvt_pk_bf16_f32 v227, v86, v87
	v_cvt_pk_bf16_f32 v228, v80, v81
	v_cvt_pk_bf16_f32 v229, v82, v83
	global_store_dwordx4 v[180:181], v[226:229], off offset:256
	s_mov_b32 s100, 0x10000
	v_lshl_add_u64 v[178:179], v[178:179], 0, s[100:101]
	s_mov_b32 s100, 0x8000
	v_lshl_add_u64 v[180:181], v[180:181], 0, s[100:101]
	s_waitcnt lgkmcnt(0)
	v_add_f32_e32 v224, v224, v230
	ds_bpermute_b32 v231, v223, v224
	s_waitcnt lgkmcnt(0)
	v_add_f32_e32 v224, v224, v231
	s_and_saveexec_b64 s[6:7], s[8:9]
	global_store_dword v[182:183], v224, off
	s_or_b64 exec, exec, s[6:7]
	s_mov_b32 s100, 0x400
	v_lshl_add_u64 v[182:183], v[182:183], 0, s[100:101]
	s_waitcnt vmcnt(25)
	v_pk_fma_f32 v[76:77], s[58:59], v[28:29], v[76:77]
	v_pk_fma_f32 v[78:79], s[16:17], v[30:31], v[78:79]
	v_pk_fma_f32 v[72:73], s[58:59], v[24:25], v[72:73]
	v_pk_fma_f32 v[74:75], s[16:17], v[26:27], v[74:75]
	v_pk_fma_f32 v[68:69], s[58:59], v[20:21], v[68:69]
	v_pk_fma_f32 v[70:71], s[16:17], v[22:23], v[70:71]
	v_pk_fma_f32 v[64:65], s[58:59], v[16:17], v[64:65]
	v_pk_fma_f32 v[66:67], s[16:17], v[18:19], v[66:67]
	global_store_dwordx4 v[178:179], v[76:79], off nt
	global_store_dwordx4 v[178:179], v[72:75], off offset:16 nt
	v_mul_f32_e32 v225, v79, v79
	v_mul_f32_e32 v224, v77, v77
	v_fmac_f32_e32 v224, v76, v76
	v_fmac_f32_e32 v225, v78, v78
	v_add_f32_e32 v224, v224, v225
	v_mul_f32_e32 v225, v73, v73
	v_fmac_f32_e32 v225, v72, v72
	v_add_f32_e32 v224, v225, v224
	v_mul_f32_e32 v225, v75, v75
	v_fmac_f32_e32 v225, v74, v74
	v_add_f32_e32 v224, v225, v224
	v_cvt_pk_bf16_f32 v226, v76, v77
	v_cvt_pk_bf16_f32 v227, v78, v79
	v_cvt_pk_bf16_f32 v228, v72, v73
	v_cvt_pk_bf16_f32 v229, v74, v75
	global_store_dwordx4 v[180:181], v[226:229], off
	global_store_dwordx4 v[178:179], v[68:71], off offset:512 nt
	global_store_dwordx4 v[178:179], v[64:67], off offset:528 nt
	v_mul_f32_e32 v232, v69, v69
	v_mul_f32_e32 v233, v71, v71
	v_fmac_f32_e32 v232, v68, v68
	v_fmac_f32_e32 v233, v70, v70
	v_add_f32_e32 v232, v232, v233
	v_mul_f32_e32 v233, v65, v65
	v_fmac_f32_e32 v233, v64, v64
	v_add_f32_e32 v232, v233, v232
	v_mul_f32_e32 v233, v67, v67
	v_fmac_f32_e32 v233, v66, v66
	v_add_f32_e32 v232, v233, v232
	v_add_f32_e32 v224, v224, v232
	ds_bpermute_b32 v230, v222, v224
	v_cvt_pk_bf16_f32 v226, v68, v69
	v_cvt_pk_bf16_f32 v227, v70, v71
	v_cvt_pk_bf16_f32 v228, v64, v65
	v_cvt_pk_bf16_f32 v229, v66, v67
	global_store_dwordx4 v[180:181], v[226:229], off offset:256
	s_mov_b32 s100, 0x10000
	v_lshl_add_u64 v[178:179], v[178:179], 0, s[100:101]
	s_mov_b32 s100, 0x8000
	v_lshl_add_u64 v[180:181], v[180:181], 0, s[100:101]
	s_waitcnt lgkmcnt(0)
	v_add_f32_e32 v224, v224, v230
	ds_bpermute_b32 v231, v223, v224
	s_waitcnt lgkmcnt(0)
	v_add_f32_e32 v224, v224, v231
	s_and_saveexec_b64 s[6:7], s[8:9]
	global_store_dword v[182:183], v224, off
	s_or_b64 exec, exec, s[6:7]
	s_mov_b32 s100, 0x400
	v_lshl_add_u64 v[182:183], v[182:183], 0, s[100:101]
	s_waitcnt vmcnt(21)
	v_pk_fma_f32 v[60:61], s[58:59], v[12:13], v[60:61]
	v_pk_fma_f32 v[62:63], s[16:17], v[14:15], v[62:63]
	v_pk_fma_f32 v[56:57], s[58:59], v[8:9], v[56:57]
	v_pk_fma_f32 v[58:59], s[16:17], v[10:11], v[58:59]
	v_pk_fma_f32 v[52:53], s[58:59], v[4:5], v[52:53]
	v_pk_fma_f32 v[54:55], s[16:17], v[6:7], v[54:55]
	v_pk_fma_f32 v[48:49], s[58:59], v[0:1], v[48:49]
	v_pk_fma_f32 v[50:51], s[16:17], v[2:3], v[50:51]
	global_store_dwordx4 v[178:179], v[60:63], off nt
	global_store_dwordx4 v[178:179], v[56:59], off offset:16 nt
	v_mul_f32_e32 v225, v63, v63
	v_mul_f32_e32 v224, v61, v61
	v_fmac_f32_e32 v224, v60, v60
	v_fmac_f32_e32 v225, v62, v62
	v_add_f32_e32 v224, v224, v225
	v_mul_f32_e32 v225, v57, v57
	v_fmac_f32_e32 v225, v56, v56
	v_add_f32_e32 v224, v225, v224
	v_mul_f32_e32 v225, v59, v59
	v_fmac_f32_e32 v225, v58, v58
	v_add_f32_e32 v224, v225, v224
	v_cvt_pk_bf16_f32 v226, v60, v61
	v_cvt_pk_bf16_f32 v227, v62, v63
	v_cvt_pk_bf16_f32 v228, v56, v57
	v_cvt_pk_bf16_f32 v229, v58, v59
	global_store_dwordx4 v[180:181], v[226:229], off
	global_store_dwordx4 v[178:179], v[52:55], off offset:512 nt
	global_store_dwordx4 v[178:179], v[48:51], off offset:528 nt
	v_mul_f32_e32 v232, v53, v53
	v_mul_f32_e32 v233, v55, v55
	v_fmac_f32_e32 v232, v52, v52
	v_fmac_f32_e32 v233, v54, v54
	v_add_f32_e32 v232, v232, v233
	v_mul_f32_e32 v233, v49, v49
	v_fmac_f32_e32 v233, v48, v48
	v_add_f32_e32 v232, v233, v232
	v_mul_f32_e32 v233, v51, v51
	v_fmac_f32_e32 v233, v50, v50
	v_add_f32_e32 v232, v233, v232
	v_add_f32_e32 v224, v224, v232
	ds_bpermute_b32 v230, v222, v224
	v_cvt_pk_bf16_f32 v226, v52, v53
	v_cvt_pk_bf16_f32 v227, v54, v55
	v_cvt_pk_bf16_f32 v228, v48, v49
	v_cvt_pk_bf16_f32 v229, v50, v51
	global_store_dwordx4 v[180:181], v[226:229], off offset:256
	s_waitcnt lgkmcnt(0)
	v_add_f32_e32 v224, v224, v230
	ds_bpermute_b32 v231, v223, v224
	s_waitcnt lgkmcnt(0)
	v_add_f32_e32 v224, v224, v231
	s_and_saveexec_b64 s[6:7], s[8:9]
	global_store_dword v[182:183], v224, off
	s_or_b64 exec, exec, s[6:7]
